# baseline (speedup 1.0000x reference)
; __device__ __forceinline__ float bf2f(u16 h) { return __uint_as_float(((unsigned)h) << 16); }
; __device__ __forceinline__ int bid_() { int b = blockIdx.x; asm volatile("" : "+s"(b)); return b; }
; __device__ __forceinline__ void phase_resid(const Params& p, const float* __restrict__ gpost, float scale, const float* __restrict__ wdt) {
;     ...
;   for (int row0 = bid_() * 8 + wid; row0 < NTOK / 2; row0 += gridDim.x * 8) {
;     uint2 fv[2][4];
;     float4 xv[2][4];
;     float sf[2] = {0.f, 0.f};
; #pragma unroll
;     for (int r = 0; r < 2; ++r) {
;       const long row = row0 + r * (NTOK / 2);
; #pragma unroll
;       for (int i = 0; i < 4; ++i) {
;         { typedef __attribute__((ext_vector_type(2))) unsigned u32x2_;
;           const u32x2_ t_ = __builtin_nontemporal_load((const u32x2_*)(L_xb + row * DM + i * 256 + lane * 4));
;           fv[r][i] = make_uint2(t_[0], t_[1]); }
;         { const f32x4 t_ = __builtin_nontemporal_load((const f32x4*)(L_out + row * DM + i * 256 + lane * 4));
;           xv[r][i] = make_float4(t_[0], t_[1], t_[2], t_[3]); }
;       }
;     }
; #pragma unroll
;     for (int r = 0; r < 2; ++r) {
; #pragma unroll
;       for (int i = 0; i < 4; ++i) {
;         const float a = bf2f((u16)(fv[r][i].x & 0xffff)), b = bf2f((u16)(fv[r][i].x >> 16));
;         const float c = bf2f((u16)(fv[r][i].y & 0xffff)), d = bf2f((u16)(fv[r][i].y >> 16));
;         sf[r] += a * a + b * b + c * c + d * d;
;       }
;       sf[r] = wave_sum(sf[r]);
.LBB0_1055:
	v_ashrrev_i32_e32 v129, 31, v128
	v_lshlrev_b64 v[16:17], 11, v[128:129]
	v_lshl_add_u64 v[58:59], v[130:131], 0, v[16:17]
	v_add_u32_e32 v178, 0x4000, v128
	flat_load_dwordx2 v[24:25], v[58:59] nt
	flat_load_dwordx2 v[26:27], v[58:59] offset:512 nt
	flat_load_dwordx2 v[28:29], v[58:59] offset:1024 nt
	v_ashrrev_i32_e32 v179, 31, v178
	flat_load_dwordx2 v[30:31], v[58:59] offset:1536 nt
	v_lshlrev_b64 v[16:17], 11, v[178:179]
	v_lshl_add_u64 v[56:57], v[130:131], 0, v[16:17]
	flat_load_dwordx2 v[40:41], v[56:57] nt
	flat_load_dwordx2 v[42:43], v[56:57] offset:512 nt
	flat_load_dwordx2 v[44:45], v[56:57] offset:1024 nt
	flat_load_dwordx2 v[46:47], v[56:57] offset:1536 nt
	v_lshlrev_b64 v[16:17], 12, v[128:129]
	v_lshl_add_u64 v[60:61], v[132:133], 0, v[16:17]
	flat_load_dwordx4 v[32:35], v[60:61] nt
	flat_load_dwordx4 v[36:39], v[60:61] offset:1024 nt
	flat_load_dwordx4 v[20:23], v[60:61] offset:2048 nt
	flat_load_dwordx4 v[16:19], v[60:61] offset:3072 nt
	s_waitcnt vmcnt(0) lgkmcnt(0)
	v_lshlrev_b32_e32 v80, 16, v24
	v_and_b32_e32 v81, 0xffff0000, v24
	v_lshlrev_b32_e32 v84, 16, v26
	v_and_b32_e32 v85, 0xffff0000, v26
	v_lshlrev_b32_e32 v82, 16, v25
	v_and_b32_e32 v83, 0xffff0000, v25
	v_lshlrev_b32_e32 v86, 16, v27
	v_and_b32_e32 v87, 0xffff0000, v27
	v_lshlrev_b32_e32 v88, 16, v28
	v_and_b32_e32 v89, 0xffff0000, v28
	v_lshlrev_b32_e32 v90, 16, v29
	v_and_b32_e32 v91, 0xffff0000, v29
	v_pk_mul_f32 v[24:25], v[80:81], v[80:81]
	v_pk_mul_f32 v[28:29], v[84:85], v[84:85]
	v_lshlrev_b32_e32 v92, 16, v30
	v_and_b32_e32 v93, 0xffff0000, v30
	v_lshlrev_b32_e32 v94, 16, v31
	v_and_b32_e32 v95, 0xffff0000, v31
	v_lshlrev_b32_e32 v78, 16, v40
	v_and_b32_e32 v79, 0xffff0000, v40
	v_lshlrev_b32_e32 v76, 16, v41
	v_and_b32_e32 v77, 0xffff0000, v41
	v_pk_mul_f32 v[26:27], v[82:83], v[82:83]
	v_pk_mul_f32 v[30:31], v[86:87], v[86:87]
	v_pk_mul_f32 v[40:41], v[88:89], v[88:89]
	v_add_f32_e32 v28, v28, v29
	v_add_f32_e32 v24, v24, v25
	v_lshlrev_b32_e32 v74, 16, v42
	v_and_b32_e32 v75, 0xffff0000, v42
	v_lshlrev_b32_e32 v72, 16, v43
	v_and_b32_e32 v73, 0xffff0000, v43
	v_lshlrev_b32_e32 v70, 16, v44
	v_and_b32_e32 v71, 0xffff0000, v44
	v_lshlrev_b32_e32 v68, 16, v45
	v_and_b32_e32 v69, 0xffff0000, v45
	v_pk_mul_f32 v[42:43], v[90:91], v[90:91]
	v_pk_mul_f32 v[44:45], v[92:93], v[92:93]
	v_add_f32_e32 v25, v40, v41
	v_add_f32_e32 v28, v30, v28
	v_add_f32_e32 v24, v26, v24
	v_lshlrev_b32_e32 v64, 16, v46
	v_and_b32_e32 v65, 0xffff0000, v46
	v_lshlrev_b32_e32 v62, 16, v47
	v_and_b32_e32 v63, 0xffff0000, v47
	v_pk_mul_f32 v[46:47], v[94:95], v[94:95]
	v_add_f32_e32 v29, v44, v45
	v_add_f32_e32 v25, v42, v25
	v_add_f32_e32 v28, v31, v28
	v_add_f32_e32 v24, v27, v24
	v_add_f32_e32 v26, v46, v29
	v_add_f32_e32 v25, v43, v25
	v_add_f32_e32 v24, v24, v28
	v_add_f32_e32 v24, v24, v25
	v_add_f32_e32 v25, v47, v26
	v_add_f32_e32 v24, v24, v25
	ds_swizzle_b32 v25, v24 offset:swizzle(SWAP,1)
	v_pk_mul_f32 v[48:49], v[78:79], v[78:79]
	v_pk_mul_f32 v[52:53], v[74:75], v[74:75]
	v_pk_mul_f32 v[50:51], v[76:77], v[76:77]
	v_pk_mul_f32 v[54:55], v[72:73], v[72:73]
	v_pk_mul_f32 v[66:67], v[70:71], v[70:71]
	v_add_f32_e32 v40, v52, v53
	v_add_f32_e32 v41, v48, v49
	v_pk_mul_f32 v[96:97], v[68:69], v[68:69]
	v_add_f32_e32 v44, v66, v67
	v_add_f32_e32 v29, v54, v40
	v_add_f32_e32 v30, v50, v41
	s_waitcnt lgkmcnt(0)
	v_add_f32_e32 v24, v24, v25
	v_add_f32_e32 v27, v55, v29
	v_add_f32_e32 v29, v51, v30
	v_add_f32_e32 v26, v96, v44
	ds_swizzle_b32 v25, v24 offset:swizzle(SWAP,2)
	v_pk_mul_f32 v[98:99], v[64:65], v[64:65]
	v_add_f32_e32 v27, v29, v27
	v_add_f32_e32 v26, v97, v26
	v_pk_mul_f32 v[100:101], v[62:63], v[62:63]
	v_add_f32_e32 v26, v27, v26
	v_add_f32_e32 v27, v98, v99
	v_add_f32_e32 v27, v100, v27
	v_add_f32_e32 v27, v101, v27
	v_add_f32_e32 v26, v26, v27
	s_waitcnt lgkmcnt(0)
	v_add_f32_e32 v28, v24, v25
	ds_swizzle_b32 v27, v26 offset:swizzle(SWAP,1)
	ds_swizzle_b32 v29, v28 offset:swizzle(SWAP,4)
	v_lshlrev_b64 v[24:25], 12, v[178:179]
	v_lshl_add_u64 v[66:67], v[132:133], 0, v[24:25]
	flat_load_dwordx4 v[52:55], v[66:67] nt
	flat_load_dwordx4 v[48:51], v[66:67] offset:1024 nt
	s_waitcnt lgkmcnt(0)
	v_add_f32_e32 v24, v26, v27
	v_add_f32_e32 v26, v28, v29
	ds_swizzle_b32 v25, v24 offset:swizzle(SWAP,2)
	ds_swizzle_b32 v27, v26 offset:swizzle(SWAP,8)
	s_waitcnt lgkmcnt(0)
	v_add_f32_e32 v40, v24, v25
	v_add_f32_e32 v42, v26, v27
	flat_load_dwordx4 v[24:27], v[66:67] offset:2048 nt
	flat_load_dwordx4 v[28:31], v[66:67] offset:3072 nt
	ds_swizzle_b32 v43, v42 offset:swizzle(SWAP,16)
	ds_swizzle_b32 v41, v40 offset:swizzle(SWAP,4)
	s_waitcnt lgkmcnt(0)
	v_add_f32_e32 v42, v42, v43
	s_nop 0
	v_readlane_b32 s24, v42, 32
	v_readlane_b32 s8, v42, 0
	v_add_f32_e32 v40, v40, v41
	v_mov_b32_e32 v42, s24
	v_add_f32_e32 v42, s8, v42
	v_fmamk_f32 v42, v42, 0x3a800000, v183
	ds_swizzle_b32 v41, v40 offset:swizzle(SWAP,8)
	v_rsq_f32_e32 v42, v42
	s_waitcnt lgkmcnt(0)
; __device__ __forceinline__ float bf2f(u16 h) { return __uint_as_float(((unsigned)h) << 16); }
; __device__ __forceinline__ float rsq_(float x) { return __builtin_amdgcn_rsqf(x); }
; __device__ __forceinline__ void phase_resid(const Params& p, const float* __restrict__ gpost, float scale, const float* __restrict__ wdt) {
;     ...
;     for (int r = 0; r < 2; ++r) {
;       const long row = row0 + r * (NTOK / 2);
;       const float rs = rsq_(sf[r] * (1.f / DM) + EPS) * scale;
;       float ss = 0.f;
; #pragma unroll
;       for (int i = 0; i < 4; ++i) {
;         const int c = i * 256 + lane * 4;
;         float4 x4 = xv[r][i];
;         const float4 gv = *(const float4*)(gpost + c);
;         x4.x += rs * bf2f((u16)(fv[r][i].x & 0xffff)) * gv.x;
;         x4.y += rs * bf2f((u16)(fv[r][i].x >> 16)) * gv.y;
;         x4.z += rs * bf2f((u16)(fv[r][i].y & 0xffff)) * gv.z;
;         x4.w += rs * bf2f((u16)(fv[r][i].y >> 16)) * gv.w;
;         { const f32x4 t_ = {x4.x, x4.y, x4.z, x4.w}; __builtin_nontemporal_store(t_, (f32x4*)(L_out + row * DM + c)); }
;         xv[r][i] = x4;
;         uint2 o; o.x = pack2(x4.x, x4.y); o.y = pack2(x4.z, x4.w);
;         *(uint2*)(L_xb + row * DM + c) = o;
;         ss += x4.x * x4.x + x4.y * x4.y + x4.z * x4.z + x4.w * x4.w;
;       }
;       ss = wave_sum(ss);
;       if (lane == 0) L_ssx[row] = ss;
;     }
	v_add_f32_e32 v96, v40, v41
	v_mul_f32_e32 v46, v173, v42
	v_pk_mul_f32 v[40:41], v[46:47], v[80:81] op_sel_hi:[0,1]
	v_pk_fma_f32 v[32:33], v[0:1], v[40:41], v[32:33]
	v_pk_mul_f32 v[40:41], v[46:47], v[82:83] op_sel_hi:[0,1]
	v_pk_fma_f32 v[34:35], v[2:3], v[40:41], v[34:35]
	v_pk_mul_f32 v[40:41], v[46:47], v[84:85] op_sel_hi:[0,1]
	v_pk_fma_f32 v[36:37], v[4:5], v[40:41], v[36:37]
	v_pk_mul_f32 v[40:41], v[46:47], v[86:87] op_sel_hi:[0,1]
	v_pk_fma_f32 v[38:39], v[6:7], v[40:41], v[38:39]
	v_pk_mul_f32 v[40:41], v[46:47], v[88:89] op_sel_hi:[0,1]
	v_pk_mul_f32 v[80:81], v[32:33], v[32:33]
	v_pk_mul_f32 v[84:85], v[36:37], v[36:37]
	v_pk_fma_f32 v[40:41], v[8:9], v[40:41], v[20:21]
	v_pk_mul_f32 v[20:21], v[46:47], v[90:91] op_sel_hi:[0,1]
	v_pk_mul_f32 v[44:45], v[46:47], v[92:93] op_sel_hi:[0,1]
	v_pk_mul_f32 v[82:83], v[34:35], v[34:35]
	v_pk_mul_f32 v[86:87], v[38:39], v[38:39]
	v_pk_fma_f32 v[42:43], v[10:11], v[20:21], v[22:23]
	v_pk_mul_f32 v[20:21], v[40:41], v[40:41]
	v_pk_fma_f32 v[44:45], v[12:13], v[44:45], v[16:17]
	v_pk_mul_f32 v[16:17], v[46:47], v[94:95] op_sel_hi:[0,1]
	v_add_f32_e32 v84, v84, v85
	v_add_f32_e32 v80, v80, v81
	v_pk_mul_f32 v[22:23], v[42:43], v[42:43]
	v_pk_fma_f32 v[46:47], v[14:15], v[16:17], v[18:19]
	v_pk_mul_f32 v[16:17], v[44:45], v[44:45]
	v_add_f32_e32 v84, v86, v84
	v_add_f32_e32 v80, v82, v80
	v_add_f32_e32 v20, v20, v21
	v_pk_mul_f32 v[18:19], v[46:47], v[46:47]
	v_add_f32_e32 v84, v87, v84
	v_add_f32_e32 v80, v83, v80
	v_add_f32_e32 v20, v22, v20
	v_add_f32_e32 v16, v16, v17
	v_add_f32_e32 v80, v80, v84
	v_add_f32_e32 v20, v23, v20
	v_add_f32_e32 v16, v18, v16
	v_add_f32_e32 v20, v20, v80
	v_add_f32_e32 v16, v19, v16
	v_add_f32_e32 v180, v16, v20
	ds_swizzle_b32 v16, v180 offset:swizzle(SWAP,1)
	ds_swizzle_b32 v97, v96 offset:swizzle(SWAP,16)
	flat_store_dwordx4 v[60:61], v[32:35] nt
	s_waitcnt lgkmcnt(0)
	v_add_f32_e32 v18, v180, v16
	ds_swizzle_b32 v19, v18 offset:swizzle(SWAP,2)
	v_add_f32_e32 v17, v96, v97
	v_cvt_pk_bf16_f32 v16, v32, v33
	v_readlane_b32 s8, v17, 0
	v_readlane_b32 s26, v17, 32
	s_waitcnt lgkmcnt(0)
	v_add_f32_e32 v18, v18, v19
	ds_swizzle_b32 v19, v18 offset:swizzle(SWAP,4)
	v_cvt_pk_bf16_f32 v17, v34, v35
	flat_store_dwordx2 v[58:59], v[16:17] nt
	v_cvt_pk_bf16_f32 v16, v36, v37
	v_cvt_pk_bf16_f32 v17, v38, v39
	s_waitcnt lgkmcnt(0)
	v_add_f32_e32 v18, v18, v19
	ds_swizzle_b32 v19, v18 offset:swizzle(SWAP,8)
	flat_store_dwordx4 v[60:61], v[36:39] offset:1024 nt
	flat_store_dwordx2 v[58:59], v[16:17] offset:512 nt
	v_cvt_pk_bf16_f32 v16, v40, v41
	v_cvt_pk_bf16_f32 v17, v42, v43
	s_waitcnt lgkmcnt(0)
	v_add_f32_e32 v18, v18, v19
	ds_swizzle_b32 v19, v18 offset:swizzle(SWAP,16)
	flat_store_dwordx4 v[60:61], v[40:43] offset:2048 nt
	flat_store_dwordx2 v[58:59], v[16:17] offset:1024 nt
	v_cvt_pk_bf16_f32 v16, v44, v45
	v_cvt_pk_bf16_f32 v17, v46, v47
	flat_store_dwordx4 v[60:61], v[44:47] offset:3072 nt
	flat_store_dwordx2 v[58:59], v[16:17] offset:1536 nt
	s_waitcnt lgkmcnt(0)
	v_add_f32_e32 v16, v18, v19
	s_nop 0
	v_readlane_b32 s27, v16, 0
	v_readlane_b32 s28, v16, 32
	s_and_saveexec_b64 s[24:25], s[0:1]
	s_cbranch_execz .LBB0_1057
	v_mov_b32_e32 v18, s28
	v_lshl_add_u64 v[16:17], v[128:129], 2, s[16:17]
	v_add_f32_e32 v18, s27, v18
	flat_store_dword v[16:17], v18
.LBB0_1057:
	s_or_b64 exec, exec, s[24:25]
	v_mov_b32_e32 v16, s26
	v_add_f32_e32 v16, s8, v16
	v_fmamk_f32 v16, v16, 0x3a800000, v183
	v_rsq_f32_e32 v16, v16
	s_nop 0
	v_mul_f32_e32 v58, v173, v16
	v_pk_mul_f32 v[16:17], v[58:59], v[78:79] op_sel_hi:[0,1]
	v_pk_mul_f32 v[20:21], v[58:59], v[74:75] op_sel_hi:[0,1]
	v_pk_mul_f32 v[18:19], v[58:59], v[76:77] op_sel_hi:[0,1]
	s_waitcnt vmcnt(0)
	v_pk_fma_f32 v[16:17], v[0:1], v[16:17], v[52:53]
	v_pk_fma_f32 v[20:21], v[4:5], v[20:21], v[48:49]
	v_pk_mul_f32 v[22:23], v[58:59], v[72:73] op_sel_hi:[0,1]
	v_pk_fma_f32 v[18:19], v[2:3], v[18:19], v[54:55]
	v_pk_mul_f32 v[52:53], v[16:17], v[16:17]
	v_pk_fma_f32 v[22:23], v[6:7], v[22:23], v[50:51]
	v_pk_mul_f32 v[48:49], v[20:21], v[20:21]
	v_pk_mul_f32 v[54:55], v[18:19], v[18:19]
	v_pk_mul_f32 v[50:51], v[22:23], v[22:23]
	v_pk_mul_f32 v[60:61], v[58:59], v[70:71] op_sel_hi:[0,1]
	v_add_f32_e32 v48, v48, v49
	v_add_f32_e32 v49, v52, v53
	v_pk_fma_f32 v[24:25], v[8:9], v[60:61], v[24:25]
	v_pk_mul_f32 v[60:61], v[58:59], v[68:69] op_sel_hi:[0,1]
	v_add_f32_e32 v48, v50, v48
	v_add_f32_e32 v49, v54, v49
	v_pk_fma_f32 v[26:27], v[10:11], v[60:61], v[26:27]
	v_pk_mul_f32 v[60:61], v[24:25], v[24:25]
	v_add_f32_e32 v48, v51, v48
	v_add_f32_e32 v49, v55, v49
	v_pk_mul_f32 v[68:69], v[26:27], v[26:27]
	v_pk_mul_f32 v[64:65], v[58:59], v[64:65] op_sel_hi:[0,1]
	v_add_f32_e32 v48, v49, v48
	v_add_f32_e32 v49, v60, v61
	v_pk_fma_f32 v[28:29], v[12:13], v[64:65], v[28:29]
	v_pk_mul_f32 v[58:59], v[58:59], v[62:63] op_sel_hi:[0,1]
	v_add_f32_e32 v49, v68, v49
	v_pk_fma_f32 v[30:31], v[14:15], v[58:59], v[30:31]
	v_pk_mul_f32 v[58:59], v[28:29], v[28:29]
	v_add_f32_e32 v49, v69, v49
	v_pk_mul_f32 v[62:63], v[30:31], v[30:31]
	v_add_f32_e32 v48, v49, v48
	v_add_f32_e32 v49, v58, v59
	v_add_f32_e32 v49, v62, v49
	v_add_f32_e32 v49, v63, v49
	v_add_f32_e32 v191, v49, v48
	ds_swizzle_b32 v48, v191 offset:swizzle(SWAP,1)
	v_cvt_pk_bf16_f32 v49, v18, v19
	flat_store_dwordx4 v[66:67], v[16:19] nt
	s_waitcnt lgkmcnt(0)
	v_add_f32_e32 v50, v191, v48
	ds_swizzle_b32 v51, v50 offset:swizzle(SWAP,2)
	v_cvt_pk_bf16_f32 v48, v16, v17
	flat_store_dwordx2 v[56:57], v[48:49] nt
	v_cvt_pk_bf16_f32 v48, v20, v21
	v_cvt_pk_bf16_f32 v49, v22, v23
	s_waitcnt lgkmcnt(0)
	v_add_f32_e32 v50, v50, v51
	ds_swizzle_b32 v51, v50 offset:swizzle(SWAP,4)
	flat_store_dwordx4 v[66:67], v[20:23] offset:1024 nt
	flat_store_dwordx2 v[56:57], v[48:49] offset:512 nt
	v_cvt_pk_bf16_f32 v48, v24, v25
	v_cvt_pk_bf16_f32 v49, v26, v27
	s_waitcnt lgkmcnt(0)
	v_add_f32_e32 v50, v50, v51
	ds_swizzle_b32 v51, v50 offset:swizzle(SWAP,8)
	flat_store_dwordx4 v[66:67], v[24:27] offset:2048 nt
	flat_store_dwordx2 v[56:57], v[48:49] offset:1024 nt
	v_cvt_pk_bf16_f32 v48, v28, v29
	v_cvt_pk_bf16_f32 v49, v30, v31
	s_waitcnt lgkmcnt(0)
	v_add_f32_e32 v50, v50, v51
	ds_swizzle_b32 v51, v50 offset:swizzle(SWAP,16)
	flat_store_dwordx4 v[66:67], v[28:31] offset:3072 nt
	flat_store_dwordx2 v[56:57], v[48:49] offset:1536 nt
	s_waitcnt lgkmcnt(0)
	v_add_f32_e32 v48, v50, v51
	s_nop 0
	v_readlane_b32 s8, v48, 0
	v_readlane_b32 s26, v48, 32
	s_and_saveexec_b64 s[24:25], s[0:1]
	s_cbranch_execz .LBB0_1059
	v_mov_b32_e32 v50, s26
	v_lshl_add_u64 v[48:49], v[178:179], 2, s[16:17]
	v_add_f32_e32 v50, s8, v50
	flat_store_dword v[48:49], v50

; template <int EPI>
; __device__ __forceinline__ void gemm_phase(const Params& p, const u16* __restrict__ A, const u16* __restrict__ Bt, int K, int nN,
;                            u16* __restrict__ Cout, int ldc) {
;     ...
; #pragma unroll
;       for (int half = 0; half < 2; ++half) {
; #pragma unroll
;         for (int mm = 0; mm < 4; ++mm) {
;           const int m = half * 4 + mm;
; #pragma unroll
;           for (int j = 0; j < 4; ++j) {
;             float rs = 1.f;
;             if (EPI == EPI_WIN) rs = rsl[wr * 128 + m * 16 + fqe * 4 + j];
;             u16* d = stg + (wr * 64 + mm * 16 + fqe * 4 + j) * 256 + (fre & 7);
; #pragma unroll
;             for (int n = 0; n < 4; ++n) {
;               const int chunk = (wc * 8 + n * 2 + (fre >> 3)) ^ (fqe << 1);
;               d[chunk * 8] = f2bf(acc[m][n][j] * rs);
;             }
;           }
;           __builtin_amdgcn_sched_barrier(0);
;         }
;         __syncthreads();
.Lss_epi:
	v_mov_b32_e32 v66, v181
	v_mov_b32_e32 v112, v173
	v_mov_b32_e32 v64, v191
	s_waitcnt vmcnt(0)
	s_waitcnt vmcnt(0) lgkmcnt(0)
	s_barrier
	s_mov_b32 s0, 0x10000
	v_and_b32_e32 v65, 7, v64
	v_lshlrev_b32_e32 v67, 1, v65
	v_add_u32_e32 v114, v64, v196
	v_lshlrev_b32_e32 v113, 4, v66
	v_lshl_or_b32 v66, v66, 11, v67
	v_and_b32_e32 v118, -8, v114
	v_add3_u32 v66, v66, v195, s0
	v_bitop3_b32 v114, v114, v113, -8 bitop3:0x6c
	v_add_u32_e32 v119, 16, v118
	v_cvt_pk_bf16_f32 v67, v128, s0
	v_lshl_add_u32 v114, v114, 1, v66
	v_xor_b32_e32 v119, v119, v113
	v_add_u32_e32 v120, 32, v118
	ds_write_b16 v114, v67
	v_cvt_pk_bf16_f32 v67, v132, s0
	v_lshl_add_u32 v119, v119, 1, v66
	v_xor_b32_e32 v120, v120, v113
	v_add_u32_e32 v118, 48, v118
	ds_write_b16 v119, v67
	v_cvt_pk_bf16_f32 v67, v136, s0
	v_lshl_add_u32 v120, v120, 1, v66
	v_xor_b32_e32 v113, v118, v113
	ds_write_b16 v120, v67
	v_cvt_pk_bf16_f32 v67, v140, s0
	v_lshl_add_u32 v113, v113, 1, v66
	v_cvt_pk_bf16_f32 v66, v129, s0
	ds_write_b16 v113, v67
	ds_write_b16 v114, v66 offset:512
	v_cvt_pk_bf16_f32 v66, v133, s0
	ds_write_b16 v119, v66 offset:512
	v_cvt_pk_bf16_f32 v66, v137, s0
	ds_write_b16 v120, v66 offset:512
	v_cvt_pk_bf16_f32 v66, v141, s0
	ds_write_b16 v113, v66 offset:512
	v_cvt_pk_bf16_f32 v66, v130, s0
	ds_write_b16 v114, v66 offset:1024
	v_cvt_pk_bf16_f32 v66, v134, s0
	ds_write_b16 v119, v66 offset:1024
	v_cvt_pk_bf16_f32 v66, v138, s0
	ds_write_b16 v120, v66 offset:1024
	v_cvt_pk_bf16_f32 v66, v142, s0
	ds_write_b16 v113, v66 offset:1024
	v_cvt_pk_bf16_f32 v66, v131, s0
	v_and_b32_e32 v64, 31, v112
	v_lshrrev_b32_e32 v65, 6, v112
	ds_write_b16 v114, v66 offset:1536
	v_cvt_pk_bf16_f32 v66, v135, s0
	v_bitop3_b32 v65, v65, v64, 6 bitop3:0x6c
	ds_write_b16 v119, v66 offset:1536
	v_cvt_pk_bf16_f32 v66, v139, s0
	v_lshl_or_b32 v115, v65, 4, v188
	v_lshl_or_b32 v64, v64, 3, s28
	v_mov_b32_e32 v65, v172
	v_ashrrev_i32_e32 v116, 5, v112
	ds_write_b16 v120, v66 offset:1536
	v_cvt_pk_bf16_f32 v66, v143, s0
	v_lshl_add_u64 v[64:65], v[64:65], 1, s[2:3]
	v_lshl_add_u32 v117, v116, 9, v115
	ds_write_b16 v113, v66 offset:1536
	v_cvt_pk_bf16_f32 v66, v108, s0
	ds_write_b16 v114, v66 offset:8192
	v_cvt_pk_bf16_f32 v66, v104, s0
	ds_write_b16 v119, v66 offset:8192
	v_cvt_pk_bf16_f32 v66, v100, s0
	ds_write_b16 v120, v66 offset:8192
	v_cvt_pk_bf16_f32 v66, v96, s0
	ds_write_b16 v113, v66 offset:8192
	v_cvt_pk_bf16_f32 v66, v109, s0
	ds_write_b16 v114, v66 offset:8704
	v_cvt_pk_bf16_f32 v66, v105, s0
	ds_write_b16 v119, v66 offset:8704
	v_cvt_pk_bf16_f32 v66, v101, s0
	ds_write_b16 v120, v66 offset:8704
	v_cvt_pk_bf16_f32 v66, v97, s0
	ds_write_b16 v113, v66 offset:8704
	v_cvt_pk_bf16_f32 v66, v110, s0
	ds_write_b16 v114, v66 offset:9216
	v_cvt_pk_bf16_f32 v66, v106, s0
	ds_write_b16 v119, v66 offset:9216
	v_cvt_pk_bf16_f32 v66, v102, s0
	ds_write_b16 v120, v66 offset:9216
	v_cvt_pk_bf16_f32 v66, v98, s0
	ds_write_b16 v113, v66 offset:9216
	v_cvt_pk_bf16_f32 v66, v111, s0
	ds_write_b16 v114, v66 offset:9728
	v_cvt_pk_bf16_f32 v66, v107, s0
	ds_write_b16 v119, v66 offset:9728
	v_cvt_pk_bf16_f32 v66, v103, s0
	ds_write_b16 v120, v66 offset:9728
	v_cvt_pk_bf16_f32 v66, v99, s0
	ds_write_b16 v113, v66 offset:9728
	v_cvt_pk_bf16_f32 v66, v92, s0
	ds_write_b16 v114, v66 offset:16384
	v_cvt_pk_bf16_f32 v66, v88, s0
	ds_write_b16 v119, v66 offset:16384
	v_cvt_pk_bf16_f32 v66, v84, s0
	ds_write_b16 v120, v66 offset:16384
	v_cvt_pk_bf16_f32 v66, v80, s0
	ds_write_b16 v113, v66 offset:16384
	v_cvt_pk_bf16_f32 v66, v93, s0
	ds_write_b16 v114, v66 offset:16896
	v_cvt_pk_bf16_f32 v66, v89, s0
	ds_write_b16 v119, v66 offset:16896
	v_cvt_pk_bf16_f32 v66, v85, s0
	ds_write_b16 v120, v66 offset:16896
	v_cvt_pk_bf16_f32 v66, v81, s0
	ds_write_b16 v113, v66 offset:16896
	v_cvt_pk_bf16_f32 v66, v94, s0
	ds_write_b16 v114, v66 offset:17408
	v_cvt_pk_bf16_f32 v66, v90, s0
	ds_write_b16 v119, v66 offset:17408
	v_cvt_pk_bf16_f32 v66, v86, s0
	ds_write_b16 v120, v66 offset:17408
	v_cvt_pk_bf16_f32 v66, v82, s0
	ds_write_b16 v113, v66 offset:17408
	v_cvt_pk_bf16_f32 v66, v95, s0
	ds_write_b16 v114, v66 offset:17920
	v_cvt_pk_bf16_f32 v66, v91, s0
	ds_write_b16 v119, v66 offset:17920
	v_cvt_pk_bf16_f32 v66, v87, s0
	ds_write_b16 v120, v66 offset:17920
	v_cvt_pk_bf16_f32 v66, v83, s0
	ds_write_b16 v113, v66 offset:17920
	v_cvt_pk_bf16_f32 v66, v76, s0
	ds_write_b16 v114, v66 offset:24576
	v_cvt_pk_bf16_f32 v66, v72, s0
	ds_write_b16 v119, v66 offset:24576
	v_cvt_pk_bf16_f32 v66, v68, s0
	ds_write_b16 v120, v66 offset:24576
	v_cvt_pk_bf16_f32 v66, v148, s0
	ds_write_b16 v113, v66 offset:24576
	v_cvt_pk_bf16_f32 v66, v77, s0
	ds_write_b16 v114, v66 offset:25088
	v_cvt_pk_bf16_f32 v66, v73, s0
	ds_write_b16 v119, v66 offset:25088
	v_cvt_pk_bf16_f32 v66, v69, s0
	ds_write_b16 v120, v66 offset:25088
	v_cvt_pk_bf16_f32 v66, v149, s0
	ds_write_b16 v113, v66 offset:25088
	v_cvt_pk_bf16_f32 v66, v78, s0
	ds_write_b16 v114, v66 offset:25600
	v_cvt_pk_bf16_f32 v66, v74, s0
	ds_write_b16 v119, v66 offset:25600
	v_cvt_pk_bf16_f32 v66, v70, s0
	ds_write_b16 v120, v66 offset:25600
	v_cvt_pk_bf16_f32 v66, v150, s0
	ds_write_b16 v113, v66 offset:25600
	v_cvt_pk_bf16_f32 v66, v79, s0
	ds_write_b16 v114, v66 offset:26112
	v_cvt_pk_bf16_f32 v66, v75, s0
	ds_write_b16 v119, v66 offset:26112
	v_cvt_pk_bf16_f32 v66, v71, s0
	ds_write_b16 v120, v66 offset:26112
	v_cvt_pk_bf16_f32 v66, v151, s0
	ds_write_b16 v113, v66 offset:26112
	v_lshrrev_b32_e32 v70, 4, v112
	s_waitcnt lgkmcnt(0)
	s_barrier
; template <int EPI>
; __device__ __forceinline__ void gemm_phase(const Params& p, const u16* __restrict__ A, const u16* __restrict__ Bt, int K, int nN,
;                            u16* __restrict__ Cout, int ldc) {
;     ...
; #pragma unroll
;         for (int it = 0; it < 8; ++it) {
;           const int id = it * 512 + tide, r = id >> 5, ck = id & 31;
;           const uint4 v = *(const uint4*)(stg + r * 256 + ((ck ^ (((r >> 2) & 3) << 1)) * 8));
;           const int grow = brow + (r >> 6) * 128 + half * 64 + (r & 63);
;           if (EPI == EPI_WIN) { typedef __attribute__((ext_vector_type(4))) unsigned u32x4_; const u32x4_ t_ = {v.x, v.y, v.z, v.w};
;             __builtin_nontemporal_store(t_, (u32x4_*)(Cout + (unsigned)grow * (unsigned)ldc + (unsigned)(bcol + ck * 8))); }
;           else *(uint4*)(Cout + (unsigned)grow * (unsigned)ldc + (unsigned)(bcol + ck * 8)) = v;
;         }
;         asm volatile("s_waitcnt lgkmcnt(0)" ::: "memory"); __builtin_amdgcn_s_barrier();
	ds_read_b128 v[66:69], v117
	v_and_b32_e32 v72, 0x3fff80, v70
	v_add_u32_e32 v70, s27, v72
	v_and_b32_e32 v73, 63, v116
	v_or_b32_e32 v70, v70, v73
	v_lshlrev_b32_e32 v70, 10, v70
	v_mov_b32_e32 v71, v172
	v_lshl_add_u64 v[70:71], v[70:71], 1, v[64:65]
	s_waitcnt lgkmcnt(0)
	flat_store_dwordx4 v[70:71], v[66:69] nt
	v_add_u32_e32 v70, 0x200, v112
	v_ashrrev_i32_e32 v71, 5, v70
	v_lshl_add_u32 v74, v71, 9, v115
	v_lshrrev_b32_e32 v70, 4, v70
	ds_read_b128 v[66:69], v74
	v_and_b32_e32 v75, 0x3fff80, v70
	v_add_u32_e32 v70, s27, v75
	v_and_b32_e32 v76, 63, v71
	v_or_b32_e32 v70, v70, v76
	v_lshlrev_b32_e32 v70, 10, v70
	v_mov_b32_e32 v71, v172
	v_lshl_add_u64 v[70:71], v[70:71], 1, v[64:65]
	s_waitcnt lgkmcnt(0)
	flat_store_dwordx4 v[70:71], v[66:69] nt
	v_add_u32_e32 v70, 0x400, v112
	v_ashrrev_i32_e32 v71, 5, v70
	v_lshl_add_u32 v77, v71, 9, v115
	v_lshrrev_b32_e32 v70, 4, v70
	ds_read_b128 v[66:69], v77
	v_and_b32_e32 v78, 0x3fff80, v70
	v_add_u32_e32 v70, s27, v78
	v_and_b32_e32 v79, 63, v71
	v_or_b32_e32 v70, v70, v79
	v_lshlrev_b32_e32 v70, 10, v70
	v_mov_b32_e32 v71, v172
	v_lshl_add_u64 v[70:71], v[70:71], 1, v[64:65]
	s_waitcnt lgkmcnt(0)
	flat_store_dwordx4 v[70:71], v[66:69] nt
	v_add_u32_e32 v70, 0x600, v112
	v_ashrrev_i32_e32 v71, 5, v70
	v_lshl_add_u32 v80, v71, 9, v115
	v_lshrrev_b32_e32 v70, 4, v70
	ds_read_b128 v[66:69], v80
	v_and_b32_e32 v81, 0x3fff80, v70
	v_add_u32_e32 v70, s27, v81
	v_and_b32_e32 v82, 63, v71
	v_or_b32_e32 v70, v70, v82
	v_lshlrev_b32_e32 v70, 10, v70
	v_mov_b32_e32 v71, v172
	v_lshl_add_u64 v[70:71], v[70:71], 1, v[64:65]
	s_waitcnt lgkmcnt(0)
	flat_store_dwordx4 v[70:71], v[66:69] nt
	v_add_u32_e32 v70, 0x800, v112
	v_ashrrev_i32_e32 v71, 5, v70
	v_lshl_add_u32 v83, v71, 9, v115
	v_lshrrev_b32_e32 v70, 4, v70
	ds_read_b128 v[66:69], v83
	v_and_b32_e32 v84, 0x3fff80, v70
	v_add_u32_e32 v70, s27, v84
	v_and_b32_e32 v85, 63, v71
	v_or_b32_e32 v70, v70, v85
	v_lshlrev_b32_e32 v70, 10, v70
	v_mov_b32_e32 v71, v172
	v_lshl_add_u64 v[70:71], v[70:71], 1, v[64:65]
	s_waitcnt lgkmcnt(0)
	flat_store_dwordx4 v[70:71], v[66:69] nt
	v_add_u32_e32 v70, 0xa00, v112
	v_ashrrev_i32_e32 v71, 5, v70
	v_lshl_add_u32 v86, v71, 9, v115
	v_lshrrev_b32_e32 v70, 4, v70
	ds_read_b128 v[66:69], v86
	v_and_b32_e32 v87, 0x3fff80, v70
	v_add_u32_e32 v70, s27, v87
	v_and_b32_e32 v88, 63, v71
	v_or_b32_e32 v70, v70, v88
	v_lshlrev_b32_e32 v70, 10, v70
	v_mov_b32_e32 v71, v172
	v_lshl_add_u64 v[70:71], v[70:71], 1, v[64:65]
	s_waitcnt lgkmcnt(0)
	flat_store_dwordx4 v[70:71], v[66:69] nt
	v_add_u32_e32 v70, 0xc00, v112
	v_ashrrev_i32_e32 v71, 5, v70
	v_lshl_add_u32 v89, v71, 9, v115
	v_lshrrev_b32_e32 v70, 4, v70
	ds_read_b128 v[66:69], v89
	v_and_b32_e32 v90, 0x3fff80, v70
	v_add_u32_e32 v70, s27, v90
	v_and_b32_e32 v91, 63, v71
	v_or_b32_e32 v70, v70, v91
	v_lshlrev_b32_e32 v70, 10, v70
	v_mov_b32_e32 v71, v172
	v_lshl_add_u64 v[70:71], v[70:71], 1, v[64:65]
	s_waitcnt lgkmcnt(0)
	flat_store_dwordx4 v[70:71], v[66:69] nt
	v_add_u32_e32 v70, 0xe00, v112
	v_ashrrev_i32_e32 v71, 5, v70
	v_lshl_add_u32 v92, v71, 9, v115
	v_lshrrev_b32_e32 v70, 4, v70
	ds_read_b128 v[66:69], v92
	v_and_b32_e32 v93, 0x3fff80, v70
	v_add_u32_e32 v70, s27, v93
	v_and_b32_e32 v94, 63, v71
	v_or_b32_e32 v70, v70, v94
	v_lshlrev_b32_e32 v70, 10, v70
	v_mov_b32_e32 v71, v172
	v_lshl_add_u64 v[70:71], v[70:71], 1, v[64:65]
	s_waitcnt lgkmcnt(0)
	flat_store_dwordx4 v[70:71], v[66:69] nt
	v_cvt_pk_bf16_f32 v48, v48, s0
	s_waitcnt lgkmcnt(0)
	s_barrier
; template <int EPI>
; __device__ __forceinline__ void gemm_phase(const Params& p, const u16* __restrict__ A, const u16* __restrict__ Bt, int K, int nN,
;                            u16* __restrict__ Cout, int ldc) {
;     ...
; #pragma unroll
;       for (int half = 0; half < 2; ++half) {
; #pragma unroll
;         for (int mm = 0; mm < 4; ++mm) {
;           const int m = half * 4 + mm;
; #pragma unroll
;           for (int j = 0; j < 4; ++j) {
;             float rs = 1.f;
;             if (EPI == EPI_WIN) rs = rsl[wr * 128 + m * 16 + fqe * 4 + j];
;             u16* d = stg + (wr * 64 + mm * 16 + fqe * 4 + j) * 256 + (fre & 7);
; #pragma unroll
;             for (int n = 0; n < 4; ++n) {
;               const int chunk = (wc * 8 + n * 2 + (fre >> 3)) ^ (fqe << 1);
;               d[chunk * 8] = f2bf(acc[m][n][j] * rs);
;             }
;           }
;           __builtin_amdgcn_sched_barrier(0);
;         }
;         __syncthreads();
; #pragma unroll
;         for (int it = 0; it < 8; ++it) {
;           const int id = it * 512 + tide, r = id >> 5, ck = id & 31;
;           const uint4 v = *(const uint4*)(stg + r * 256 + ((ck ^ (((r >> 2) & 3) << 1)) * 8));
;           const int grow = brow + (r >> 6) * 128 + half * 64 + (r & 63);
;           if (EPI == EPI_WIN) { typedef __attribute__((ext_vector_type(4))) unsigned u32x4_; const u32x4_ t_ = {v.x, v.y, v.z, v.w};
;             __builtin_nontemporal_store(t_, (u32x4_*)(Cout + (unsigned)grow * (unsigned)ldc + (unsigned)(bcol + ck * 8))); }
;           else *(uint4*)(Cout + (unsigned)grow * (unsigned)ldc + (unsigned)(bcol + ck * 8)) = v;
;         }
;         asm volatile("s_waitcnt lgkmcnt(0)" ::: "memory"); __builtin_amdgcn_s_barrier();
	v_cvt_pk_bf16_f32 v56, v56, s0
	v_cvt_pk_bf16_f32 v52, v52, s0
	ds_write_b16 v113, v48
	v_cvt_pk_bf16_f32 v48, v61, s0
	v_cvt_pk_bf16_f32 v60, v60, s0
	ds_write_b16 v119, v56
	ds_write_b16 v120, v52
	ds_write_b16 v114, v48 offset:512
	v_cvt_pk_bf16_f32 v48, v57, s0
	ds_write_b16 v114, v60
	ds_write_b16 v119, v48 offset:512
	v_cvt_pk_bf16_f32 v48, v53, s0
	ds_write_b16 v120, v48 offset:512
	v_cvt_pk_bf16_f32 v48, v49, s0
	ds_write_b16 v113, v48 offset:512
	v_cvt_pk_bf16_f32 v48, v62, s0
	ds_write_b16 v114, v48 offset:1024
	v_cvt_pk_bf16_f32 v48, v58, s0
	ds_write_b16 v119, v48 offset:1024
	v_cvt_pk_bf16_f32 v48, v54, s0
	ds_write_b16 v120, v48 offset:1024
	v_cvt_pk_bf16_f32 v48, v50, s0
	ds_write_b16 v113, v48 offset:1024
	v_cvt_pk_bf16_f32 v48, v63, s0
	ds_write_b16 v114, v48 offset:1536
	v_cvt_pk_bf16_f32 v48, v59, s0
	ds_write_b16 v119, v48 offset:1536
	v_cvt_pk_bf16_f32 v48, v55, s0
	ds_write_b16 v120, v48 offset:1536
	v_cvt_pk_bf16_f32 v48, v51, s0
	ds_write_b16 v113, v48 offset:1536
	v_cvt_pk_bf16_f32 v32, v32, s0
	v_cvt_pk_bf16_f32 v40, v40, s0
	v_cvt_pk_bf16_f32 v36, v36, s0
	ds_write_b16 v113, v32 offset:8192
	v_cvt_pk_bf16_f32 v32, v45, s0
	v_cvt_pk_bf16_f32 v44, v44, s0
	ds_write_b16 v119, v40 offset:8192
	ds_write_b16 v120, v36 offset:8192
	ds_write_b16 v114, v32 offset:8704
	v_cvt_pk_bf16_f32 v32, v41, s0
	ds_write_b16 v114, v44 offset:8192
	ds_write_b16 v119, v32 offset:8704
	v_cvt_pk_bf16_f32 v32, v37, s0
	ds_write_b16 v120, v32 offset:8704
	v_cvt_pk_bf16_f32 v32, v33, s0
	ds_write_b16 v113, v32 offset:8704
	v_cvt_pk_bf16_f32 v32, v46, s0
	ds_write_b16 v114, v32 offset:9216
	v_cvt_pk_bf16_f32 v32, v42, s0
	ds_write_b16 v119, v32 offset:9216
	v_cvt_pk_bf16_f32 v32, v38, s0
	ds_write_b16 v120, v32 offset:9216
	v_cvt_pk_bf16_f32 v32, v34, s0
	ds_write_b16 v113, v32 offset:9216
	v_cvt_pk_bf16_f32 v32, v47, s0
	ds_write_b16 v114, v32 offset:9728
	v_cvt_pk_bf16_f32 v32, v43, s0
	ds_write_b16 v119, v32 offset:9728
	v_cvt_pk_bf16_f32 v32, v39, s0
	ds_write_b16 v120, v32 offset:9728
	v_cvt_pk_bf16_f32 v32, v35, s0
	ds_write_b16 v113, v32 offset:9728
	v_cvt_pk_bf16_f32 v16, v16, s0
	v_cvt_pk_bf16_f32 v24, v24, s0
	v_cvt_pk_bf16_f32 v20, v20, s0
	ds_write_b16 v113, v16 offset:16384
	v_cvt_pk_bf16_f32 v16, v29, s0
	v_cvt_pk_bf16_f32 v28, v28, s0
	ds_write_b16 v119, v24 offset:16384
	ds_write_b16 v120, v20 offset:16384
	ds_write_b16 v114, v16 offset:16896
	v_cvt_pk_bf16_f32 v16, v25, s0
	ds_write_b16 v114, v28 offset:16384
	ds_write_b16 v119, v16 offset:16896
	v_cvt_pk_bf16_f32 v16, v21, s0
	ds_write_b16 v120, v16 offset:16896
	v_cvt_pk_bf16_f32 v16, v17, s0
	ds_write_b16 v113, v16 offset:16896
	v_cvt_pk_bf16_f32 v16, v30, s0
	ds_write_b16 v114, v16 offset:17408
	v_cvt_pk_bf16_f32 v16, v26, s0
	ds_write_b16 v119, v16 offset:17408
	v_cvt_pk_bf16_f32 v16, v22, s0
	ds_write_b16 v120, v16 offset:17408
	v_cvt_pk_bf16_f32 v16, v18, s0
	ds_write_b16 v113, v16 offset:17408
	v_cvt_pk_bf16_f32 v16, v31, s0
	ds_write_b16 v114, v16 offset:17920
	v_cvt_pk_bf16_f32 v16, v27, s0
	ds_write_b16 v119, v16 offset:17920
	v_cvt_pk_bf16_f32 v16, v23, s0
	ds_write_b16 v120, v16 offset:17920
	v_cvt_pk_bf16_f32 v16, v19, s0
	ds_write_b16 v113, v16 offset:17920
	v_cvt_pk_bf16_f32 v0, v0, s0
	v_cvt_pk_bf16_f32 v8, v8, s0
	v_cvt_pk_bf16_f32 v4, v4, s0
	ds_write_b16 v113, v0 offset:24576
	v_cvt_pk_bf16_f32 v0, v13, s0
	v_cvt_pk_bf16_f32 v12, v12, s0
	ds_write_b16 v119, v8 offset:24576
	ds_write_b16 v120, v4 offset:24576
	ds_write_b16 v114, v0 offset:25088
	v_cvt_pk_bf16_f32 v0, v9, s0
	ds_write_b16 v114, v12 offset:24576
	ds_write_b16 v119, v0 offset:25088
	v_cvt_pk_bf16_f32 v0, v5, s0
	ds_write_b16 v120, v0 offset:25088
	v_cvt_pk_bf16_f32 v0, v1, s0
	ds_write_b16 v113, v0 offset:25088
	v_cvt_pk_bf16_f32 v0, v14, s0
	ds_write_b16 v114, v0 offset:25600
	v_cvt_pk_bf16_f32 v0, v10, s0
	ds_write_b16 v119, v0 offset:25600
	v_cvt_pk_bf16_f32 v0, v6, s0
	ds_write_b16 v120, v0 offset:25600
	v_cvt_pk_bf16_f32 v0, v2, s0
	ds_write_b16 v113, v0 offset:25600
	v_cvt_pk_bf16_f32 v0, v15, s0
	ds_write_b16 v114, v0 offset:26112
	v_cvt_pk_bf16_f32 v0, v11, s0
	ds_write_b16 v119, v0 offset:26112
	v_cvt_pk_bf16_f32 v0, v7, s0
	ds_write_b16 v120, v0 offset:26112
	v_cvt_pk_bf16_f32 v0, v3, s0
	ds_write_b16 v113, v0 offset:26112
	s_waitcnt lgkmcnt(0)
	s_barrier
	s_or_b32 s0, s27, 64
	ds_read_b128 v[0:3], v117
	v_add_u32_e32 v4, s0, v72
	v_or_b32_e32 v4, v4, v73
	v_lshlrev_b32_e32 v4, 10, v4
	v_mov_b32_e32 v5, v172
	v_lshl_add_u64 v[4:5], v[4:5], 1, v[64:65]
	s_waitcnt lgkmcnt(0)
	flat_store_dwordx4 v[4:5], v[0:3] nt
	ds_read_b128 v[0:3], v74
	v_add_u32_e32 v4, s0, v75
	v_or_b32_e32 v4, v4, v76
	v_lshlrev_b32_e32 v4, 10, v4
	v_mov_b32_e32 v5, v172
	v_lshl_add_u64 v[4:5], v[4:5], 1, v[64:65]
	s_waitcnt lgkmcnt(0)
	flat_store_dwordx4 v[4:5], v[0:3] nt
	ds_read_b128 v[0:3], v77
	v_add_u32_e32 v4, s0, v78
	v_or_b32_e32 v4, v4, v79
	v_lshlrev_b32_e32 v4, 10, v4
	v_mov_b32_e32 v5, v172
	v_lshl_add_u64 v[4:5], v[4:5], 1, v[64:65]
	s_waitcnt lgkmcnt(0)
	flat_store_dwordx4 v[4:5], v[0:3] nt
	ds_read_b128 v[0:3], v80
	v_add_u32_e32 v4, s0, v81
	v_or_b32_e32 v4, v4, v82
	v_lshlrev_b32_e32 v4, 10, v4
	v_mov_b32_e32 v5, v172
	v_lshl_add_u64 v[4:5], v[4:5], 1, v[64:65]
	s_waitcnt lgkmcnt(0)
	flat_store_dwordx4 v[4:5], v[0:3] nt
	ds_read_b128 v[0:3], v83
	v_add_u32_e32 v4, s0, v84
	v_or_b32_e32 v4, v4, v85
	v_lshlrev_b32_e32 v4, 10, v4
	v_mov_b32_e32 v5, v172
	v_lshl_add_u64 v[4:5], v[4:5], 1, v[64:65]
	s_waitcnt lgkmcnt(0)
	flat_store_dwordx4 v[4:5], v[0:3] nt
	ds_read_b128 v[0:3], v86
	v_add_u32_e32 v4, s0, v87
	v_or_b32_e32 v4, v4, v88
	v_lshlrev_b32_e32 v4, 10, v4
	v_mov_b32_e32 v5, v172
	v_lshl_add_u64 v[4:5], v[4:5], 1, v[64:65]
	s_waitcnt lgkmcnt(0)
	flat_store_dwordx4 v[4:5], v[0:3] nt
	ds_read_b128 v[0:3], v89
	v_add_u32_e32 v4, s0, v90
	v_or_b32_e32 v4, v4, v91
	v_lshlrev_b32_e32 v4, 10, v4
	v_mov_b32_e32 v5, v172
	v_lshl_add_u64 v[4:5], v[4:5], 1, v[64:65]
	s_waitcnt lgkmcnt(0)
	flat_store_dwordx4 v[4:5], v[0:3] nt
	ds_read_b128 v[0:3], v92
	v_add_u32_e32 v4, s0, v93
	v_or_b32_e32 v4, v4, v94
	v_lshlrev_b32_e32 v4, 10, v4
	v_mov_b32_e32 v5, v172
	v_lshl_add_u64 v[4:5], v[4:5], 1, v[64:65]
	s_waitcnt lgkmcnt(0)
	flat_store_dwordx4 v[4:5], v[0:3] nt
	s_waitcnt lgkmcnt(0)
	s_mov_b64 s[0:1], -1
	s_and_b64 vcc, exec, s[4:5]
	s_barrier
	s_cbranch_vccnz .LBB0_1122
